# dilated attention: bias-table load no longer waited before Q loads (overlapped with Q global loads)
# baseline (speedup 1.0000x reference)
; #define LAS __attribute__((address_space(3)))
; DI const bf16* dil_hm(Frame& F, int which, int b, int h, int pos) { return (const bf16*)(F.ws + WS_BIG) + (size_t)which * MTOK * 2048 + ((size_t)(b * 16 + h) * SEQ + pos) * 128; }
; template <int D, int STR>
; DI void load_q_frags(Frame& F, bf16x8* qf, const bf16* g0, size_t gstride, LAS unsigned char* buf) {
;     constexpr int CPR = D / 8, NCH = 256 * CPR / NTHR;
;     __syncthreads();
;     int tid_ = F.tid; asm volatile("" : "+v"(tid_));
; #pragma unroll
;     for (int hb = 0; hb < NCH; hb += 4) { u32x4 v[4];
; #pragma unroll
;       for (int k = 0; k < 4; ++k) { const int c = tid_ + (hb + k) * NTHR, r = c / CPR, q = c % CPR; v[k] = *(const u32x4*)(g0 + (size_t)r * gstride + q * 8); }
; #pragma unroll
;       for (int k = 0; k < 4; ++k) { const int c = tid_ + (hb + k) * NTHR, r = c / CPR, q = c % CPR; *(LAS u32x4*)(buf + r * STR + q * 16) = v[k]; } }
;     __syncthreads();
; DI void dil_unit(Frame& F, const DilItem& it, bool has_next, const DilItem& nx, RowRegs<128>& RK, RowRegs<128>& RV) {
;     ...
;     { const float* bd = (const float*)(F.ws + WS_BIASDIL) + (g * 16 + h) * 160;
;       if (F.tid <= 128) tb[128 - F.tid] = bd[F.tid]; }
;     bf16x8 qf[8];
;     const size_t tok0 = (size_t)b * SEQ + (size_t)m0 * d + r;
;     load_q_frags<128, KSTR128>(F, qf, dil_hm(F, 0, b, h, m0 * d + r), (size_t)d * 128, Ks);
.LBB0_1090:
	s_and_b32 s60, s6, 15
	s_waitcnt vmcnt(0)
	s_barrier
	s_mov_b64 s[100:101], s[0:1]
	s_and_saveexec_b64 s[30:31], s[0:1]
	s_cbranch_execz .LBB0_1092
	s_lshl_b32 s12, s61, 4
	s_or_b32 s12, s12, s60
	s_mulk_i32 s12, 0xa0
	v_lshl_add_u64 v[0:1], s[12:13], 2, v[150:151]
	global_load_dword v64, v[0:1], off
.LBB0_1092:
	s_or_b64 exec, exec, s[30:31]
	s_cmp_lg_u32 s61, 0
	s_cselect_b64 s[38:39], -1, 0
	s_and_b32 s12, s36, 15
	s_cmp_eq_u32 s61, 1
	s_cselect_b64 s[30:31], -1, 0
	s_and_b64 s[40:41], s[30:31], exec
	s_cselect_b32 s41, 2, 4
	s_cselect_b32 s44, 9, 11
	s_cmp_eq_u32 s37, 1
	s_cselect_b32 s36, 2, 4
	s_cselect_b32 s40, 9, 11
	s_cmp_eq_u32 s37, 0
	s_cselect_b32 s46, 0, s36
	s_cselect_b32 s40, 7, s40
	s_cmp_eq_u32 s61, 0
	s_cselect_b64 s[36:37], -1, 0
	s_and_b64 s[42:43], s[36:37], exec
	s_cselect_b32 s43, 0, s41
	s_cselect_b32 s44, 7, s44
	s_lshr_b32 s48, 16, s43
	s_sub_i32 s41, 4, s43
	s_add_i32 s48, s48, -1
	s_lshr_b32 s41, s12, s41
	s_and_b32 s48, s48, s12
	s_lshr_b32 s12, 16, s46
	s_and_b32 s7, s7, 15
	s_add_i32 s12, s12, -1
	s_ashr_i32 s62, s47, 4
	s_and_b32 s63, s47, 15
	s_sub_i32 s47, 4, s46
	s_and_b32 s49, s12, s7
	s_lshl_b32 s12, s48, 8
	s_lshr_b32 s47, s7, s47
	s_lshl_b32 s7, s12, s43
	v_mov_b32_e32 v28, v146
	s_or_b32 s64, s7, s41
	s_ashr_i32 s7, s6, 31
	s_waitcnt lgkmcnt(0)
	s_barrier
	s_ashr_i32 s42, s6, 4
	v_ashrrev_i32_e32 v0, 31, v28
	s_lshl_b64 s[6:7], s[6:7], 20
	v_lshrrev_b32_e32 v0, 28, v0
	s_add_u32 s6, s24, s6
	v_add_u32_e32 v0, v28, v0
	s_addc_u32 s7, s25, s7
	s_lshl_b32 s64, s64, 8
	v_ashrrev_i32_e32 v32, 4, v0
	v_and_b32_e32 v0, -16, v0
	v_sub_u32_e32 v48, v28, v0
	v_ashrrev_i32_e32 v33, 31, v32
	s_add_u32 s6, s6, s64
	s_addc_u32 s7, s7, 0
	v_lshlrev_b64 v[0:1], s44, v[32:33]
	v_lshlrev_b32_e32 v2, 3, v48
	v_lshl_add_u64 v[0:1], v[0:1], 1, s[6:7]
	v_ashrrev_i32_e32 v3, 31, v2
	v_lshl_add_u64 v[0:1], v[2:3], 1, v[0:1]
	v_add_u32_e32 v2, 0x200, v28
	v_ashrrev_i32_e32 v3, 31, v2
	v_add_u32_e32 v8, 0x400, v28
	v_lshrrev_b32_e32 v3, 28, v3
	v_ashrrev_i32_e32 v9, 31, v8
	v_add_u32_e32 v3, v2, v3
	v_lshrrev_b32_e32 v9, 28, v9
	v_ashrrev_i32_e32 v34, 4, v3
	v_add_u32_e32 v9, v8, v9
	v_and_b32_e32 v3, -16, v3
	v_ashrrev_i32_e32 v35, 31, v34
	v_ashrrev_i32_e32 v36, 4, v9
	v_and_b32_e32 v9, -16, v9
	v_sub_u32_e32 v33, v2, v3
	v_lshlrev_b64 v[2:3], s44, v[34:35]
	v_sub_u32_e32 v35, v8, v9
	v_ashrrev_i32_e32 v37, 31, v36
	v_lshlrev_b64 v[8:9], s44, v[36:37]
	v_lshlrev_b32_e32 v10, 3, v35
	v_lshl_add_u64 v[8:9], v[8:9], 1, s[6:7]
	v_ashrrev_i32_e32 v11, 31, v10
	v_lshl_add_u64 v[8:9], v[10:11], 1, v[8:9]
	v_add_u32_e32 v10, 0x600, v28
	v_ashrrev_i32_e32 v11, 31, v10
	v_add_u32_e32 v16, 0x800, v28
	v_lshrrev_b32_e32 v11, 28, v11
	v_ashrrev_i32_e32 v17, 31, v16
	v_add_u32_e32 v11, v10, v11
	v_lshrrev_b32_e32 v17, 28, v17
	v_ashrrev_i32_e32 v38, 4, v11
	v_add_u32_e32 v17, v16, v17
	v_and_b32_e32 v11, -16, v11
	v_ashrrev_i32_e32 v39, 31, v38
	v_ashrrev_i32_e32 v40, 4, v17
	v_and_b32_e32 v17, -16, v17
	v_sub_u32_e32 v37, v10, v11
	v_lshlrev_b64 v[10:11], s44, v[38:39]
	v_sub_u32_e32 v39, v16, v17
	v_ashrrev_i32_e32 v41, 31, v40
	v_lshlrev_b32_e32 v4, 3, v33
	v_lshlrev_b64 v[16:17], s44, v[40:41]
	v_lshlrev_b32_e32 v18, 3, v39
	v_lshl_add_u64 v[2:3], v[2:3], 1, s[6:7]
	v_ashrrev_i32_e32 v5, 31, v4
	v_lshl_add_u64 v[16:17], v[16:17], 1, s[6:7]
	v_ashrrev_i32_e32 v19, 31, v18
	v_lshl_add_u64 v[4:5], v[4:5], 1, v[2:3]
	v_lshl_add_u64 v[16:17], v[18:19], 1, v[16:17]
	v_add_u32_e32 v18, 0xa00, v28
	global_load_dwordx4 v[0:3], v[0:1], off
	s_nop 0
	global_load_dwordx4 v[4:7], v[4:5], off
	v_ashrrev_i32_e32 v19, 31, v18
	v_lshlrev_b32_e32 v12, 3, v37
	v_lshrrev_b32_e32 v19, 28, v19
	v_lshl_add_u64 v[10:11], v[10:11], 1, s[6:7]
	v_ashrrev_i32_e32 v13, 31, v12
	v_add_u32_e32 v19, v18, v19
	v_add_u32_e32 v24, 0xc00, v28
	v_lshl_add_u64 v[12:13], v[12:13], 1, v[10:11]
	v_ashrrev_i32_e32 v42, 4, v19
	v_and_b32_e32 v19, -16, v19
	v_ashrrev_i32_e32 v25, 31, v24
	global_load_dwordx4 v[8:11], v[8:9], off
	s_nop 0
	global_load_dwordx4 v[12:15], v[12:13], off
	v_sub_u32_e32 v41, v18, v19
	v_ashrrev_i32_e32 v43, 31, v42
	v_lshrrev_b32_e32 v25, 28, v25
	v_add_u32_e32 v28, 0xe00, v28
	v_lshlrev_b64 v[18:19], s44, v[42:43]
	v_lshlrev_b32_e32 v20, 3, v41
	v_add_u32_e32 v25, v24, v25
	v_ashrrev_i32_e32 v29, 31, v28
	v_lshl_add_u64 v[18:19], v[18:19], 1, s[6:7]
	v_ashrrev_i32_e32 v21, 31, v20
	v_ashrrev_i32_e32 v44, 4, v25
	v_and_b32_e32 v25, -16, v25
	v_lshrrev_b32_e32 v29, 28, v29
	v_lshl_add_u64 v[20:21], v[20:21], 1, v[18:19]
	v_sub_u32_e32 v43, v24, v25
	v_ashrrev_i32_e32 v45, 31, v44
	v_add_u32_e32 v29, v28, v29
	global_load_dwordx4 v[16:19], v[16:17], off
	s_nop 0
	global_load_dwordx4 v[20:23], v[20:21], off
	v_lshlrev_b64 v[24:25], s44, v[44:45]
	v_lshlrev_b32_e32 v26, 3, v43
	v_ashrrev_i32_e32 v46, 4, v29
	v_and_b32_e32 v29, -16, v29
	v_lshl_add_u64 v[24:25], v[24:25], 1, s[6:7]
	v_ashrrev_i32_e32 v27, 31, v26
	v_sub_u32_e32 v45, v28, v29
	v_ashrrev_i32_e32 v47, 31, v46
	v_lshl_add_u64 v[24:25], v[26:27], 1, v[24:25]
	v_lshlrev_b64 v[28:29], s44, v[46:47]
	v_lshlrev_b32_e32 v30, 3, v45
	global_load_dwordx4 v[24:27], v[24:25], off
	v_lshl_add_u64 v[28:29], v[28:29], 1, s[6:7]
	v_ashrrev_i32_e32 v31, 31, v30
	v_lshl_add_u64 v[28:29], v[30:31], 1, v[28:29]
	global_load_dwordx4 v[28:31], v[28:29], off
	v_mul_lo_u32 v32, v32, s45
	v_lshlrev_b32_e32 v47, 4, v48
	v_add3_u32 v32, 0, v32, v47
	s_cmp_eq_u32 s48, 0
	s_cselect_b64 s[6:7], -1, 0
	v_mov_b32_e32 v161, 0
	v_mov_b32_e32 v160, 0xf149f2ca
	s_mov_b64 s[98:99], exec
	s_mov_b64 exec, s[100:101]
	s_waitcnt vmcnt(8)
	ds_write_b32 v147, v64
	s_mov_b64 exec, s[98:99]
	s_waitcnt vmcnt(7)
	ds_write_b128 v32, v[0:3]
	v_mul_lo_u32 v0, v34, s45
	v_lshlrev_b32_e32 v1, 4, v33
	v_add3_u32 v0, 0, v0, v1
	s_waitcnt vmcnt(6)
	ds_write_b128 v0, v[4:7]
	v_mul_lo_u32 v0, v36, s45
	v_lshlrev_b32_e32 v1, 4, v35
	v_add3_u32 v0, 0, v0, v1
	v_lshlrev_b32_e32 v1, 4, v37
	v_mov_b32_e32 v2, v149
	v_mov_b32_e32 v3, v149
	v_mov_b32_e32 v4, v149
	s_waitcnt vmcnt(5)
	ds_write_b128 v0, v[8:11]
	v_mul_lo_u32 v0, v38, s45
	v_add3_u32 v0, 0, v0, v1
	s_waitcnt vmcnt(4)
	ds_write_b128 v0, v[12:15]
	v_mul_lo_u32 v0, v40, s45
	v_lshlrev_b32_e32 v1, 4, v39
	v_add3_u32 v0, 0, v0, v1
	v_lshlrev_b32_e32 v1, 4, v41
	v_mov_b32_e32 v14, v149
	v_mov_b32_e32 v15, v149
	v_mov_b32_e32 v5, v149
	v_mov_b32_e32 v6, v149
	v_mov_b32_e32 v7, v149
	v_mov_b32_e32 v8, v149
	v_mov_b32_e32 v9, v149
	v_mov_b32_e32 v10, v149
	v_mov_b32_e32 v11, v149
	v_mov_b32_e32 v12, v149
	s_waitcnt vmcnt(3)
	ds_write_b128 v0, v[16:19]
	v_mul_lo_u32 v0, v42, s45
	v_add3_u32 v0, 0, v0, v1
	s_waitcnt vmcnt(2)
	ds_write_b128 v0, v[20:23]
	v_mul_lo_u32 v0, v44, s45
	v_lshlrev_b32_e32 v1, 4, v43
	v_add3_u32 v0, 0, v0, v1
	v_lshlrev_b32_e32 v1, 4, v45
	v_mov_b32_e32 v13, v149
	s_waitcnt vmcnt(1)
	ds_write_b128 v0, v[24:27]
	v_mul_lo_u32 v0, v46, s45
	v_add3_u32 v0, 0, v0, v1
	s_waitcnt vmcnt(0)
	ds_write_b128 v0, v[28:31]
	v_mov_b32_e32 v0, v144
	s_waitcnt lgkmcnt(0)
	s_barrier
; #define LAS __attribute__((address_space(3)))
; template <int D, int STR>
; DI void load_q_frags(Frame& F, bf16x8* qf, const bf16* g0, size_t gstride, LAS unsigned char* buf) {
;     ...
;     int lane_ = F.lane; asm volatile("" : "+v"(lane_));
;     LAS const unsigned char* qp = buf + (32 * F.wave + (lane_ & 31)) * STR + 16 * (lane_ >> 5);
; #pragma unroll
;     for (int st = 0; st < D / 16; ++st) qf[st] = *(LAS const bf16x8*)(qp + 32 * st);
; DI void dil_unit(Frame& F, const DilItem& it, bool has_next, const DilItem& nx, RowRegs<128>& RK, RowRegs<128>& RV) {
;     ...
;     f32x16 acc[4];
; #pragma unroll
;     for (int e = 0; e < 4; ++e)
; #pragma unroll
;         for (int i = 0; i < 16; ++i) acc[e][i] = 0.f;
;     float m = -1e30f, l = 0.f;
;     const int st_lo = (nb == 0 ? 1 : 0);
	s_nop 0
	v_and_or_b32 v1, v0, 31, s33
	v_ashrrev_i32_e32 v0, 1, v0
	v_mul_lo_u32 v1, v1, s45
	v_and_b32_e32 v0, -16, v0
	v_add3_u32 v0, 0, v1, v0
	ds_read_b128 v[112:115], v0
	ds_read_b128 v[116:119], v0 offset:32
	ds_read_b128 v[120:123], v0 offset:64
	ds_read_b128 v[124:127], v0 offset:96
	ds_read_b128 v[128:131], v0 offset:128
	ds_read_b128 v[132:135], v0 offset:160
	ds_read_b128 v[136:139], v0 offset:192
	ds_read_b128 v[140:143], v0 offset:224
	v_cndmask_b32_e64 v0, 0, 1, s[6:7]
	s_lshl_b32 s6, s49, 8
	s_cmp_eq_u32 s49, 0
	s_cselect_b32 s7, 0, 0xffffff80
	s_add_i32 s7, s7, s6
	s_lshl_b32 s6, s7, s46
	s_or_b32 s64, s6, s47
	v_readfirstlane_b32 s6, v0
	v_readfirstlane_b32 s66, v0
	s_lshl_b32 s6, s6, 7
	v_mov_b32_e32 v0, v149
	v_mov_b32_e32 v1, v149
	v_mov_b64_e32 v[30:31], v[14:15]
	v_mov_b64_e32 v[46:47], v[14:15]
	v_mov_b64_e32 v[62:63], v[14:15]
	v_add_lshl_u32 v192, v187, s6, 2
	s_sub_i32 s65, s33, s6
	v_mov_b64_e32 v[28:29], v[12:13]
	v_mov_b64_e32 v[26:27], v[10:11]
	v_mov_b64_e32 v[24:25], v[8:9]
	v_mov_b64_e32 v[22:23], v[6:7]
	v_mov_b64_e32 v[20:21], v[4:5]
	v_mov_b64_e32 v[18:19], v[2:3]
	v_mov_b64_e32 v[16:17], v[0:1]
	v_mov_b64_e32 v[44:45], v[12:13]
	v_mov_b64_e32 v[42:43], v[10:11]
	v_mov_b64_e32 v[40:41], v[8:9]
	v_mov_b64_e32 v[38:39], v[6:7]
	v_mov_b64_e32 v[36:37], v[4:5]
	v_mov_b64_e32 v[34:35], v[2:3]
	v_mov_b64_e32 v[32:33], v[0:1]
	v_mov_b64_e32 v[60:61], v[12:13]
	v_mov_b64_e32 v[58:59], v[10:11]
	v_mov_b64_e32 v[56:57], v[8:9]
	v_mov_b64_e32 v[54:55], v[6:7]
	v_mov_b64_e32 v[52:53], v[4:5]
	v_mov_b64_e32 v[50:51], v[2:3]
	v_mov_b64_e32 v[48:49], v[0:1]

; #define LAS __attribute__((address_space(3)))
; DI const bf16* dil_hm(Frame& F, int which, int b, int h, int pos) { return (const bf16*)(F.ws + WS_BIG) + (size_t)which * MTOK * 2048 + ((size_t)(b * 16 + h) * SEQ + pos) * 128; }
; template <int D, int STR>
; DI void load_q_frags(Frame& F, bf16x8* qf, const bf16* g0, size_t gstride, LAS unsigned char* buf) {
;     constexpr int CPR = D / 8, NCH = 256 * CPR / NTHR;
;     __syncthreads();
;     int tid_ = F.tid; asm volatile("" : "+v"(tid_));
; #pragma unroll
;     for (int hb = 0; hb < NCH; hb += 4) { u32x4 v[4];
; #pragma unroll
;       for (int k = 0; k < 4; ++k) { const int c = tid_ + (hb + k) * NTHR, r = c / CPR, q = c % CPR; v[k] = *(const u32x4*)(g0 + (size_t)r * gstride + q * 8); }
; #pragma unroll
;       for (int k = 0; k < 4; ++k) { const int c = tid_ + (hb + k) * NTHR, r = c / CPR, q = c % CPR; *(LAS u32x4*)(buf + r * STR + q * 16) = v[k]; } }
;     __syncthreads();
; DI void dil_unit(Frame& F, const DilItem& it, bool has_next, const DilItem& nx, RowRegs<128>& RK, RowRegs<128>& RV) {
;     ...
;     { const float* bd = (const float*)(F.ws + WS_BIASDIL) + (g * 16 + h) * 160;
;       if (F.tid <= 128) tb[128 - F.tid] = bd[F.tid]; }
;     bf16x8 qf[8];
;     const size_t tok0 = (size_t)b * SEQ + (size_t)m0 * d + r;
;     load_q_frags<128, KSTR128>(F, qf, dil_hm(F, 0, b, h, m0 * d + r), (size_t)d * 128, Ks);
.LBB0_1177:
	s_bfe_u32 s55, s19, 0x40004
	s_waitcnt vmcnt(0)
	s_barrier
	s_mov_b64 s[100:101], s[0:1]
	s_and_saveexec_b64 s[28:29], s[0:1]
	s_cbranch_execz .LBB0_1179
	s_mul_i32 s8, s55, 0x280
	v_lshl_add_u64 v[0:1], v[150:151], 0, s[8:9]
	global_load_dword v64, v[0:1], off
.LBB0_1179:
	s_or_b64 exec, exec, s[28:29]
	s_and_b32 s29, s19, 15
	s_ashr_i32 s28, s19, 8
	s_and_b32 s19, s5, 15
	s_cmp_eq_u32 s34, 1
	s_cselect_b32 s5, 2, 4
	s_cselect_b32 s8, 9, 11
	s_cmp_eq_u32 s34, 0
	s_cselect_b32 s5, 0, s5
	s_cselect_b32 s8, 7, s8
	s_lshr_b32 s34, 16, s5
	s_add_i32 s34, s34, -1
	s_and_b32 s39, s34, s19
	s_lshl_b32 s34, s28, 4
	s_sub_i32 s35, 4, s5
	s_or_b32 s34, s34, s55
	v_mov_b32_e32 v28, v146
	s_lshr_b32 s38, s19, s35
	s_ashr_i32 s35, s34, 31
	s_waitcnt lgkmcnt(0)
	s_barrier
	s_lshl_b32 s19, s29, 8
	v_ashrrev_i32_e32 v0, 31, v28
	s_lshl_b64 s[34:35], s[34:35], 20
	v_lshrrev_b32_e32 v0, 28, v0
	s_add_u32 s36, s24, s34
	v_add_u32_e32 v0, v28, v0
	s_addc_u32 s37, s25, s35
	s_lshl_b32 s40, s29, 16
	v_ashrrev_i32_e32 v32, 4, v0
	v_and_b32_e32 v0, -16, v0
	s_add_u32 s36, s36, s40
	v_sub_u32_e32 v48, v28, v0
	v_ashrrev_i32_e32 v33, 31, v32
	s_addc_u32 s37, s37, 0
	v_lshlrev_b64 v[0:1], 8, v[32:33]
	v_lshlrev_b32_e32 v2, 3, v48
	v_lshl_add_u64 v[0:1], s[36:37], 0, v[0:1]
	v_ashrrev_i32_e32 v3, 31, v2
	v_lshl_add_u64 v[0:1], v[2:3], 1, v[0:1]
	v_add_u32_e32 v2, 0x200, v28
	v_ashrrev_i32_e32 v3, 31, v2
	v_add_u32_e32 v8, 0x400, v28
	v_lshrrev_b32_e32 v3, 28, v3
	v_ashrrev_i32_e32 v9, 31, v8
	v_add_u32_e32 v3, v2, v3
	v_lshrrev_b32_e32 v9, 28, v9
	v_ashrrev_i32_e32 v34, 4, v3
	v_add_u32_e32 v9, v8, v9
	v_and_b32_e32 v3, -16, v3
	v_ashrrev_i32_e32 v35, 31, v34
	v_ashrrev_i32_e32 v36, 4, v9
	v_and_b32_e32 v9, -16, v9
	v_sub_u32_e32 v33, v2, v3
	v_lshlrev_b64 v[2:3], 8, v[34:35]
	v_sub_u32_e32 v35, v8, v9
	v_ashrrev_i32_e32 v37, 31, v36
	v_lshlrev_b64 v[8:9], 8, v[36:37]
	v_lshlrev_b32_e32 v10, 3, v35
	v_lshl_add_u64 v[8:9], s[36:37], 0, v[8:9]
	v_ashrrev_i32_e32 v11, 31, v10
	v_lshl_add_u64 v[8:9], v[10:11], 1, v[8:9]
	v_add_u32_e32 v10, 0x600, v28
	v_ashrrev_i32_e32 v11, 31, v10
	v_add_u32_e32 v16, 0x800, v28
	v_lshrrev_b32_e32 v11, 28, v11
	v_ashrrev_i32_e32 v17, 31, v16
	v_add_u32_e32 v11, v10, v11
	v_lshrrev_b32_e32 v17, 28, v17
	v_ashrrev_i32_e32 v38, 4, v11
	v_add_u32_e32 v17, v16, v17
	v_and_b32_e32 v11, -16, v11
	v_ashrrev_i32_e32 v39, 31, v38
	v_ashrrev_i32_e32 v40, 4, v17
	v_and_b32_e32 v17, -16, v17
	v_sub_u32_e32 v37, v10, v11
	v_lshlrev_b64 v[10:11], 8, v[38:39]
	v_sub_u32_e32 v39, v16, v17
	v_ashrrev_i32_e32 v41, 31, v40
	v_lshlrev_b32_e32 v4, 3, v33
	v_lshlrev_b64 v[16:17], 8, v[40:41]
	v_lshlrev_b32_e32 v18, 3, v39
	v_lshl_add_u64 v[2:3], s[36:37], 0, v[2:3]
	v_ashrrev_i32_e32 v5, 31, v4
	v_lshl_add_u64 v[16:17], s[36:37], 0, v[16:17]
	v_ashrrev_i32_e32 v19, 31, v18
	v_lshl_add_u64 v[4:5], v[4:5], 1, v[2:3]
	v_lshl_add_u64 v[16:17], v[18:19], 1, v[16:17]
	v_add_u32_e32 v18, 0xa00, v28
	global_load_dwordx4 v[0:3], v[0:1], off
	s_nop 0
	global_load_dwordx4 v[4:7], v[4:5], off
	v_ashrrev_i32_e32 v19, 31, v18
	v_lshlrev_b32_e32 v12, 3, v37
	v_lshrrev_b32_e32 v19, 28, v19
	v_lshl_add_u64 v[10:11], s[36:37], 0, v[10:11]
	v_ashrrev_i32_e32 v13, 31, v12
	v_add_u32_e32 v19, v18, v19
	v_add_u32_e32 v24, 0xc00, v28
	v_lshl_add_u64 v[12:13], v[12:13], 1, v[10:11]
	v_ashrrev_i32_e32 v42, 4, v19
	v_and_b32_e32 v19, -16, v19
	v_ashrrev_i32_e32 v25, 31, v24
	global_load_dwordx4 v[8:11], v[8:9], off
	s_nop 0
	global_load_dwordx4 v[12:15], v[12:13], off
	v_sub_u32_e32 v41, v18, v19
	v_ashrrev_i32_e32 v43, 31, v42
	v_lshrrev_b32_e32 v25, 28, v25
	v_add_u32_e32 v28, 0xe00, v28
	v_lshlrev_b64 v[18:19], 8, v[42:43]
	v_lshlrev_b32_e32 v20, 3, v41
	v_add_u32_e32 v25, v24, v25
	v_ashrrev_i32_e32 v29, 31, v28
	v_lshl_add_u64 v[18:19], s[36:37], 0, v[18:19]
	v_ashrrev_i32_e32 v21, 31, v20
	v_ashrrev_i32_e32 v44, 4, v25
	v_and_b32_e32 v25, -16, v25
	v_lshrrev_b32_e32 v29, 28, v29
	v_lshl_add_u64 v[20:21], v[20:21], 1, v[18:19]
	v_sub_u32_e32 v43, v24, v25
	v_ashrrev_i32_e32 v45, 31, v44
	v_add_u32_e32 v29, v28, v29
	global_load_dwordx4 v[16:19], v[16:17], off
	s_nop 0
	global_load_dwordx4 v[20:23], v[20:21], off
	v_lshlrev_b64 v[24:25], 8, v[44:45]
	v_lshlrev_b32_e32 v26, 3, v43
	v_ashrrev_i32_e32 v46, 4, v29
	v_and_b32_e32 v29, -16, v29
	v_lshl_add_u64 v[24:25], s[36:37], 0, v[24:25]
	v_ashrrev_i32_e32 v27, 31, v26
	v_sub_u32_e32 v45, v28, v29
	v_ashrrev_i32_e32 v47, 31, v46
	v_lshl_add_u64 v[24:25], v[26:27], 1, v[24:25]
	v_lshlrev_b64 v[28:29], 8, v[46:47]
	v_lshlrev_b32_e32 v30, 3, v45
	global_load_dwordx4 v[24:27], v[24:25], off
	v_lshl_add_u64 v[28:29], s[36:37], 0, v[28:29]
	v_ashrrev_i32_e32 v31, 31, v30
	v_lshl_add_u64 v[28:29], v[30:31], 1, v[28:29]
	global_load_dwordx4 v[28:31], v[28:29], off
	v_mul_lo_u32 v32, v32, s44
	v_lshlrev_b32_e32 v47, 4, v48
	v_add3_u32 v32, 0, v32, v47
	s_cmp_eq_u32 s29, 0
	s_cselect_b64 s[36:37], -1, 0
	s_lshl_b32 s29, s39, 8
	s_cmp_eq_u32 s39, 0
	v_mov_b32_e32 v161, 0
	v_mov_b32_e32 v160, 0xf149f2ca
	s_mov_b64 s[98:99], exec
	s_mov_b64 exec, s[100:101]
	s_waitcnt vmcnt(8)
	ds_write_b32 v145, v64
	s_mov_b64 exec, s[98:99]
	s_waitcnt vmcnt(7)
	ds_write_b128 v32, v[0:3]
	v_mul_lo_u32 v0, v34, s44
	v_lshlrev_b32_e32 v1, 4, v33
	v_add3_u32 v0, 0, v0, v1
	s_waitcnt vmcnt(6)
	ds_write_b128 v0, v[4:7]
	v_mul_lo_u32 v0, v36, s44
	v_lshlrev_b32_e32 v1, 4, v35
	v_add3_u32 v0, 0, v0, v1
	v_lshlrev_b32_e32 v1, 4, v37
	v_mov_b32_e32 v2, v149
	v_mov_b32_e32 v3, v149
	v_mov_b32_e32 v4, v149
	s_waitcnt vmcnt(5)
	ds_write_b128 v0, v[8:11]
	v_mul_lo_u32 v0, v38, s44
	v_add3_u32 v0, 0, v0, v1
	s_waitcnt vmcnt(4)
	ds_write_b128 v0, v[12:15]
	v_mul_lo_u32 v0, v40, s44
	v_lshlrev_b32_e32 v1, 4, v39
	v_add3_u32 v0, 0, v0, v1
	v_lshlrev_b32_e32 v1, 4, v41
	v_mov_b32_e32 v14, v149
	v_mov_b32_e32 v15, v149
	v_mov_b32_e32 v5, v149
	v_mov_b32_e32 v6, v149
	v_mov_b32_e32 v7, v149
	v_mov_b32_e32 v8, v149
	v_mov_b32_e32 v9, v149
	v_mov_b32_e32 v10, v149
	v_mov_b32_e32 v11, v149
	v_mov_b32_e32 v12, v149
	s_waitcnt vmcnt(3)
	ds_write_b128 v0, v[16:19]
	v_mul_lo_u32 v0, v42, s44
	v_add3_u32 v0, 0, v0, v1
	s_waitcnt vmcnt(2)
	ds_write_b128 v0, v[20:23]
	v_mul_lo_u32 v0, v44, s44
	v_lshlrev_b32_e32 v1, 4, v43
	v_add3_u32 v0, 0, v0, v1
	v_lshlrev_b32_e32 v1, 4, v45
	v_mov_b32_e32 v13, v149
	s_waitcnt vmcnt(1)
	ds_write_b128 v0, v[24:27]
	v_mul_lo_u32 v0, v46, s44
	v_add3_u32 v0, 0, v0, v1
	s_waitcnt vmcnt(0)
	ds_write_b128 v0, v[28:31]
	v_mov_b32_e32 v0, v144
	s_waitcnt lgkmcnt(0)
	s_barrier
; #define LAS __attribute__((address_space(3)))
; template <int D, int STR>
; DI void load_q_frags(Frame& F, bf16x8* qf, const bf16* g0, size_t gstride, LAS unsigned char* buf) {
;     ...
;     int lane_ = F.lane; asm volatile("" : "+v"(lane_));
;     LAS const unsigned char* qp = buf + (32 * F.wave + (lane_ & 31)) * STR + 16 * (lane_ >> 5);
; #pragma unroll
;     for (int st = 0; st < D / 16; ++st) qf[st] = *(LAS const bf16x8*)(qp + 32 * st);
; DI void dil_unit(Frame& F, const DilItem& it, bool has_next, const DilItem& nx, RowRegs<128>& RK, RowRegs<128>& RV) {
;     ...
;     f32x16 acc[4];
; #pragma unroll
;     for (int e = 0; e < 4; ++e)
; #pragma unroll
;         for (int i = 0; i < 16; ++i) acc[e][i] = 0.f;
;     float m = -1e30f, l = 0.f;
;     const int st_lo = (nb == 0 ? 1 : 0);
	s_nop 0
	v_and_or_b32 v1, v0, 31, s33
	v_ashrrev_i32_e32 v0, 1, v0
	v_mul_lo_u32 v1, v1, s44
	v_and_b32_e32 v0, -16, v0
	v_add3_u32 v0, 0, v1, v0
	ds_read_b128 v[112:115], v0
	ds_read_b128 v[116:119], v0 offset:32
	ds_read_b128 v[120:123], v0 offset:64
	ds_read_b128 v[124:127], v0 offset:96
	ds_read_b128 v[128:131], v0 offset:128
	ds_read_b128 v[132:135], v0 offset:160
	ds_read_b128 v[136:139], v0 offset:192
	ds_read_b128 v[140:143], v0 offset:224
	v_cndmask_b32_e64 v0, 0, 1, s[36:37]
	s_cselect_b32 s36, 0, 0xffffff80
	s_add_i32 s36, s36, s29
	s_lshl_b32 s5, s36, s5
	s_or_b32 s29, s5, s38
	s_ashr_i32 s5, s4, 31
	s_lshl_b64 s[36:37], s[4:5], 20
	v_readfirstlane_b32 s4, v0
	v_readfirstlane_b32 s57, v0
	s_lshl_b32 s4, s4, 7
	v_mov_b32_e32 v0, v149
	v_mov_b32_e32 v1, v149
	v_mov_b64_e32 v[30:31], v[14:15]
	v_mov_b64_e32 v[46:47], v[14:15]
	v_mov_b64_e32 v[62:63], v[14:15]
	v_add_lshl_u32 v191, v186, s4, 2
	s_sub_i32 s56, s33, s4
	v_mov_b64_e32 v[28:29], v[12:13]
	v_mov_b64_e32 v[26:27], v[10:11]
	v_mov_b64_e32 v[24:25], v[8:9]
	v_mov_b64_e32 v[22:23], v[6:7]
	v_mov_b64_e32 v[20:21], v[4:5]
	v_mov_b64_e32 v[18:19], v[2:3]
	v_mov_b64_e32 v[16:17], v[0:1]
	v_mov_b64_e32 v[44:45], v[12:13]
	v_mov_b64_e32 v[42:43], v[10:11]
	v_mov_b64_e32 v[40:41], v[8:9]
	v_mov_b64_e32 v[38:39], v[6:7]
	v_mov_b64_e32 v[36:37], v[4:5]
	v_mov_b64_e32 v[34:35], v[2:3]
	v_mov_b64_e32 v[32:33], v[0:1]
	v_mov_b64_e32 v[60:61], v[12:13]
	v_mov_b64_e32 v[58:59], v[10:11]
	v_mov_b64_e32 v[56:57], v[8:9]
	v_mov_b64_e32 v[54:55], v[6:7]
	v_mov_b64_e32 v[52:53], v[4:5]
	v_mov_b64_e32 v[50:51], v[2:3]
	v_mov_b64_e32 v[48:49], v[0:1]
